# SB loops: 28 dead VALU instructions removed (lane-address arithmetic left from the bpermute->permlane change, dead copies) on top of clamp merge and address hoist; later loops kept at their addresses
# baseline (speedup 1.0000x reference)
; template <bool DIAG>
; DEV void sb_tile(const char* lk, const char* lv, const int ko0, const int vo0, const bf16x8 (&qf)[8], f32x16 (&O)[4], float& accp,
;                  const int l31, const int hh) {
;   f32x16 z;
;   for (int g = 0; g < 16; ++g) z[g] = 0.f;
;   {
;     bf16x8 kf[8];
; #pragma unroll
;     for (int s = 0; s < 8; ++s) kf[s] = *(const bf16x8*)(lk + (ko0 ^ (32 * s)));
;     __builtin_amdgcn_sched_barrier(0);
; #pragma unroll
;     for (int s = 0; s < 8; ++s) z = mfma32(kf[s], qf[s], z);
;   }
;   bf16x8 vf[4][2];
; #pragma unroll
;   for (int d = 0; d < 4; ++d) { vf[d][0] = *(const bf16x8*)(lv + d * 4096 + vo0); vf[d][1] = *(const bf16x8*)(lv + d * 4096 + (vo0 ^ 32)); }
;   __builtin_amdgcn_sched_barrier(0);
;   float be[16], om[16];
; #pragma unroll
;   for (int g = 0; g < 16; ++g) {
;     const float e = __builtin_amdgcn_exp2f(fminf(-z[g], 120.f));
;     be[g] = __builtin_amdgcn_rcpf(1.f + e);
;     om[g] = e * be[g];
;     if (DIAG) { const int kl = (g & 3) + 8 * (g >> 2) + 4 * hh; if (kl >= l31) { be[g] = 0.f; om[g] = 1.f; } }
;   }
;   float gp[4], pp[4], tot[4];
; #pragma unroll
;   for (int q = 0; q < 4; ++q) { gp[q] = (om[4 * q] * om[4 * q + 1]) * (om[4 * q + 2] * om[4 * q + 3]); pp[q] = __shfl_xor(gp[q], 32); tot[q] = gp[q] * pp[q]; }
;   float suf[4];
;   suf[3] = accp; suf[2] = suf[3] * tot[3]; suf[1] = suf[2] * tot[2]; suf[0] = suf[1] * tot[1];
;   accp = suf[0] * tot[0];
;   f32x16 w;
; #pragma unroll
;   for (int q = 0; q < 4; ++q) {
;     float a = suf[q] * (hh == 0 ? pp[q] : 1.f);
;     w[4 * q + 3] = be[4 * q + 3] * a; a *= om[4 * q + 3];
;     w[4 * q + 2] = be[4 * q + 2] * a; a *= om[4 * q + 2];
;     w[4 * q + 1] = be[4 * q + 1] * a; a *= om[4 * q + 1];
; DEV void sb_block(const Params& p, int item) {
;     ...
;   for (int n = 0; n < nsteps; ++n) {
;     const int j = nsteps - 1 - n, buf = n & 3;
;     asm volatile("s_waitcnt vmcnt(8)" ::: "memory");
;     __builtin_amdgcn_s_barrier();
;     asm volatile("" ::: "memory");
;     { const int jn = j > 3 ? j - 3 : 0; SB_DMA(jn, (n + 3) & 3); }
;     const char* lb_ = smem + buf * 32768;
;     int ko0 = KO0, vo0 = VO0;
;     asm volatile("" : "+v"(ko0), "+v"(vo0));
;     if (2 * j + 1 == qt) sb_tile<true>(lb_ + 32 * 256, lb_, ko0, vo0 ^ 64, qf, O, accp, l31, hh);
;     else if (2 * j + 1 < qt) sb_tile<false>(lb_ + 32 * 256, lb_, ko0, vo0 ^ 64, qf, O, accp, l31, hh);
.LBB0_559:
	s_and_b32 s0, s33, 0x18000
	s_add_i32 s92, s0, 0
	v_add_u32_e32 v240, s92, v228
	v_add_u32_e32 v241, s92, v229
	v_add_u32_e32 v242, s92, v230
	v_add_u32_e32 v243, s92, v231
	v_add_u32_e32 v244, s92, v232
	v_add_u32_e32 v245, s92, v233
	v_add_u32_e32 v246, s92, v234
	v_add_u32_e32 v247, s92, v235
	v_add_u32_e32 v248, s92, v236
	v_add_u32_e32 v249, s92, v237
	v_add_u32_e32 v250, s92, v238
	v_add_u32_e32 v251, s92, v239
	s_add_i32 s0, s74, s69
	s_cmp_lg_u32 s89, s69
	s_mov_b64 s[66:67], -1
	s_cbranch_scc0 .LBB0_563
	s_add_i32 s1, s0, 7
	s_cmp_ge_i32 s1, s75
	s_cbranch_scc1 .Lsb_skip_A0
	ds_read_b128 v[64:67], v240 offset:8192
	ds_read_b128 v[80:83], v241 offset:8192
	ds_read_b128 v[84:87], v242 offset:8192
	ds_read_b128 v[88:91], v243 offset:8192
	ds_read_b128 v[92:95], v244 offset:8192
	ds_read_b128 v[96:99], v245 offset:8192
	ds_read_b128 v[100:103], v246 offset:8192
	ds_read_b128 v[104:107], v247 offset:8192
	s_waitcnt lgkmcnt(0)
	v_mfma_f32_32x32x16_bf16 v[64:79], v[64:67], v[128:131], 0
	v_mfma_f32_32x32x16_bf16 v[64:79], v[80:83], v[132:135], v[64:79]
	v_mfma_f32_32x32x16_bf16 v[64:79], v[84:87], v[136:139], v[64:79]
	v_mfma_f32_32x32x16_bf16 v[64:79], v[88:91], v[140:143], v[64:79]
	v_mfma_f32_32x32x16_bf16 v[64:79], v[92:95], v[144:147], v[64:79]
	v_mfma_f32_32x32x16_bf16 v[64:79], v[96:99], v[148:151], v[64:79]
	v_mfma_f32_32x32x16_bf16 v[64:79], v[100:103], v[152:155], v[64:79]
	ds_read_b128 v[84:87], v250
	ds_read_b128 v[96:99], v250 offset:4096
	ds_read_b128 v[80:83], v251
	ds_read_b128 v[100:103], v251 offset:4096
	ds_read_b128 v[112:115], v250 offset:8192
	ds_read_b128 v[164:167], v250 offset:12288
	ds_read_b128 v[116:119], v251 offset:8192
	ds_read_b128 v[160:163], v251 offset:12288
	v_mfma_f32_32x32x16_bf16 v[64:79], v[104:107], v[156:159], v[64:79]
	s_nop 11
	v_min_f32_e64 v68, -v68, s32
	v_exp_f32_e32 v90, v68
	v_min_f32_e64 v68, -v69, s32
	v_exp_f32_e32 v91, v68
	v_add_f32_e32 v68, 1.0, v90
	v_min_f32_e64 v73, -v73, s32
	v_add_f32_e32 v69, 1.0, v91
	v_rcp_f32_e32 v68, v68
	v_rcp_f32_e32 v69, v69
	v_exp_f32_e32 v104, v73
	v_min_f32_e64 v73, -v74, s32
	v_min_f32_e64 v74, -v75, s32
	v_min_f32_e64 v72, -v72, s32
	v_min_f32_e64 v75, -v77, s32
	v_min_f32_e64 v77, -v79, s32
	v_exp_f32_e32 v72, v72
	v_exp_f32_e32 v105, v74
	v_min_f32_e64 v74, -v76, s32
	v_exp_f32_e32 v76, v75
	v_min_f32_e64 v75, -v78, s32
	v_pk_mul_f32 v[90:91], v[90:91], v[68:69]
	v_exp_f32_e32 v73, v73
	v_pk_mul_f32 v[78:79], v[90:91], v[90:91] op_sel_hi:[0,1]
	v_add_f32_e32 v78, 1.0, v72
	v_rcp_f32_e32 v108, v78
	v_add_f32_e32 v78, 1.0, v104
	v_rcp_f32_e32 v110, v78
	v_add_f32_e32 v78, 1.0, v73
	v_rcp_f32_e32 v109, v78
	v_add_f32_e32 v78, 1.0, v105
	v_rcp_f32_e32 v111, v78
	v_exp_f32_e32 v74, v74
	v_exp_f32_e32 v75, v75
	v_exp_f32_e32 v77, v77
	v_pk_mul_f32 v[72:73], v[72:73], v[108:109]
	v_pk_mul_f32 v[104:105], v[104:105], v[110:111]
	v_pk_mul_f32 v[120:121], v[72:73], v[104:105]
	v_add_f32_e32 v72, 1.0, v74
	v_rcp_f32_e32 v122, v72
	v_add_f32_e32 v72, 1.0, v76
	v_rcp_f32_e32 v124, v72
	v_add_f32_e32 v72, 1.0, v75
	v_min_f32_e64 v70, -v70, s32
	v_rcp_f32_e32 v123, v72
	v_add_f32_e32 v72, 1.0, v77
	v_exp_f32_e32 v92, v70
	v_rcp_f32_e32 v125, v72
	v_min_f32_e64 v70, -v71, s32
	v_min_f32_e64 v67, -v67, s32
	v_exp_f32_e32 v93, v70
	v_min_f32_e64 v64, -v64, s32
	v_exp_f32_e32 v196, v67
	v_exp_f32_e32 v88, v64
	v_pk_mul_f32 v[74:75], v[74:75], v[122:123]
	v_pk_mul_f32 v[76:77], v[76:77], v[124:125]
	v_add_f32_e32 v70, 1.0, v92
	v_pk_mul_f32 v[126:127], v[74:75], v[76:77]
	v_add_f32_e32 v71, 1.0, v93
	v_mul_f32_e32 v72, v126, v127
	v_add_f32_e32 v67, 1.0, v196
	v_rcp_f32_e32 v70, v70
	v_rcp_f32_e32 v71, v71
	v_pk_mul_f32 v[120:121], v[120:121], v[120:121] op_sel:[0,1] op_sel_hi:[1,0]
	v_mov_b32_e32 v74, v72
	s_nop 1
	v_permlane32_swap_b32_e32 v72, v74
	v_add_f32_e32 v64, 1.0, v88
	v_min_f32_e64 v66, -v66, s32
	v_rcp_f32_e32 v67, v67
	v_mov_b32_e32 v121, v120
	s_nop 1
	v_permlane32_swap_b32_e32 v120, v121
	v_rcp_f32_e32 v64, v64
	v_min_f32_e64 v65, -v65, s32
	v_exp_f32_e32 v94, v66
	v_exp_f32_e32 v169, v65
	v_pk_mul_f32 v[92:93], v[92:93], v[70:71]
	s_waitcnt lgkmcnt(0)
	v_mul_f32_e32 v127, v72, v74
	v_pk_mul_f32 v[106:107], v[92:93], v[92:93] op_sel_hi:[0,1]
	v_mov_b32_e32 v126, v67
	v_add_f32_e32 v66, 1.0, v94
	v_mov_b32_e32 v89, v79
	v_cndmask_b32_e64 v72, 1.0, v121, s[10:11]
	v_mov_b32_e32 v78, v109
	v_mov_b32_e32 v79, v111
	v_mov_b32_e32 v109, v110
	v_pk_mul_f32 v[110:111], v[196:197], v[126:127]
	v_mov_b32_e32 v106, v64
	v_add_f32_e32 v65, 1.0, v169
	v_rcp_f32_e32 v66, v66
	v_mul_f32_e32 v127, v72, v111
	v_pk_mul_f32 v[88:89], v[88:89], v[106:107]
	v_rcp_f32_e32 v65, v65
	v_mul_f32_e32 v126, v105, v127
	v_mov_b32_e32 v105, v89
	s_nop 1
	v_permlane32_swap_b32_e32 v89, v105
	v_mov_b32_e32 v95, v120
	v_mov_b32_e32 v120, v66
	v_mul_f32_e32 v73, v73, v126
	v_pk_mul_f32 v[94:95], v[94:95], v[120:121]
	v_mul_f32_e32 v72, v104, v73
	v_mul_f32_e32 v104, v169, v65
	v_pk_mul_f32 v[120:121], v[94:95], v[110:111]
	s_waitcnt lgkmcnt(0)
	v_pk_mul_f32 v[88:89], v[88:89], v[104:105]
	v_cndmask_b32_e64 v90, 1.0, v105, s[10:11]
	v_pk_mul_f32 v[88:89], v[88:89], v[120:121]
	v_mov_b32_e32 v95, v88
	s_nop 1
	v_permlane32_swap_b32_e32 v88, v95
	v_cndmask_b32_e64 v74, 1.0, v74, s[10:11]
	v_pk_mul_f32 v[78:79], v[78:79], v[126:127]
	v_pk_mul_f32 v[72:73], v[108:109], v[72:73]
	v_cvt_pk_bf16_f32 v209, v78, v79
	s_waitcnt lgkmcnt(0)
	v_mul_f32_e32 v88, v88, v95
	v_mul_f32_e32 v199, v88, v89
	v_cndmask_b32_e64 v88, 1.0, v95, s[10:11]
	v_mul_f32_e32 v89, v88, v89
	v_mul_f32_e32 v88, v110, v89
	v_pk_mul_f32 v[66:67], v[66:67], v[88:89]
	v_mul_f32_e32 v89, v90, v121
	v_mul_f32_e32 v95, v94, v88
	v_mul_f32_e32 v88, v93, v89
	v_mul_f32_e32 v93, v92, v88
	v_mul_f32_e32 v92, v91, v93
	v_mul_f32_e32 v91, v197, v74
	v_mul_f32_e32 v90, v77, v91
	v_mul_f32_e32 v94, v104, v95
	v_mul_f32_e32 v75, v75, v90
	v_pk_mul_f32 v[64:65], v[64:65], v[94:95]
	v_pk_mul_f32 v[68:69], v[68:69], v[92:93]
	v_pk_mul_f32 v[70:71], v[70:71], v[88:89]
	v_mov_b32_e32 v88, v123
	v_mov_b32_e32 v123, v124
	v_mul_f32_e32 v74, v76, v75
	v_pk_mul_f32 v[74:75], v[122:123], v[74:75]
	v_cvt_pk_bf16_f32 v170, v64, v65
	v_cvt_pk_bf16_f32 v171, v66, v67
	v_cvt_pk_bf16_f32 v172, v68, v69
	v_cvt_pk_bf16_f32 v173, v70, v71
	v_cvt_pk_bf16_f32 v208, v72, v73
	v_cvt_pk_bf16_f32 v210, v74, v75
	v_mfma_f32_32x32x16_bf16 v[64:79], v[84:87], v[170:173], v[48:63]
	v_mov_b32_e32 v89, v125
	v_mul_f32_e64 v88, v88, v90
	v_mul_f32_e64 v89, v89, v91
	v_cvt_pk_bf16_f32 v211, v88, v89
	s_nop 1
	v_mfma_f32_32x32x16_bf16 v[64:79], v[80:83], v[208:211], v[64:79]
	v_mfma_f32_32x32x16_bf16 v[80:95], v[96:99], v[170:173], v[32:47]
	v_mfma_f32_32x32x16_bf16 v[80:95], v[100:103], v[208:211], v[80:95]
	v_mfma_f32_32x32x16_bf16 v[96:111], v[112:115], v[170:173], v[16:31]
	v_mfma_f32_32x32x16_bf16 v[96:111], v[116:119], v[208:211], v[96:111]
	v_mfma_f32_32x32x16_bf16 v[112:127], v[164:167], v[170:173], v[0:15]
	v_mfma_f32_32x32x16_bf16 v[112:127], v[160:163], v[208:211], v[112:127]

; DEV f32x16 mfma32(bf16x8 a, bf16x8 b, f32x16 c) { return __builtin_amdgcn_mfma_f32_32x32x16_bf16(a, b, c, 0, 0, 0); }
; template <bool DIAG>
; DEV void sb_tile(const char* lk, const char* lv, const int ko0, const int vo0, const bf16x8 (&qf)[8], f32x16 (&O)[4], float& accp,
;                  const int l31, const int hh) {
;   f32x16 z;
;   for (int g = 0; g < 16; ++g) z[g] = 0.f;
;   {
;     bf16x8 kf[8];
; #pragma unroll
;     for (int s = 0; s < 8; ++s) kf[s] = *(const bf16x8*)(lk + (ko0 ^ (32 * s)));
;     __builtin_amdgcn_sched_barrier(0);
; #pragma unroll
;     for (int s = 0; s < 8; ++s) z = mfma32(kf[s], qf[s], z);
;   }
;   bf16x8 vf[4][2];
; #pragma unroll
;   for (int d = 0; d < 4; ++d) { vf[d][0] = *(const bf16x8*)(lv + d * 4096 + vo0); vf[d][1] = *(const bf16x8*)(lv + d * 4096 + (vo0 ^ 32)); }
;   __builtin_amdgcn_sched_barrier(0);
;   float be[16], om[16];
; #pragma unroll
;   for (int g = 0; g < 16; ++g) {
;     const float e = __builtin_amdgcn_exp2f(fminf(-z[g], 120.f));
;     be[g] = __builtin_amdgcn_rcpf(1.f + e);
;     om[g] = e * be[g];
;     if (DIAG) { const int kl = (g & 3) + 8 * (g >> 2) + 4 * hh; if (kl >= l31) { be[g] = 0.f; om[g] = 1.f; } }
;   }
;   float gp[4], pp[4], tot[4];
; #pragma unroll
;   for (int q = 0; q < 4; ++q) { gp[q] = (om[4 * q] * om[4 * q + 1]) * (om[4 * q + 2] * om[4 * q + 3]); pp[q] = __shfl_xor(gp[q], 32); tot[q] = gp[q] * pp[q]; }
;   float suf[4];
;   suf[3] = accp; suf[2] = suf[3] * tot[3]; suf[1] = suf[2] * tot[2]; suf[0] = suf[1] * tot[1];
;   accp = suf[0] * tot[0];
;   f32x16 w;
; #pragma unroll
;   for (int q = 0; q < 4; ++q) {
;     float a = suf[q] * (hh == 0 ? pp[q] : 1.f);
.LBB0_563:
	s_andn2_b64 vcc, exec, s[66:67]
	s_cbranch_vccnz .LBB0_565
	ds_read_b128 v[64:67], v240 offset:8192
	ds_read_b128 v[80:83], v241 offset:8192
	ds_read_b128 v[84:87], v242 offset:8192
	ds_read_b128 v[88:91], v243 offset:8192
	ds_read_b128 v[92:95], v244 offset:8192
	ds_read_b128 v[96:99], v245 offset:8192
	ds_read_b128 v[100:103], v246 offset:8192
	ds_read_b128 v[112:115], v247 offset:8192
	s_waitcnt lgkmcnt(0)
	v_mfma_f32_32x32x16_bf16 v[64:79], v[64:67], v[128:131], 0
	v_mfma_f32_32x32x16_bf16 v[64:79], v[80:83], v[132:135], v[64:79]
	v_mfma_f32_32x32x16_bf16 v[64:79], v[84:87], v[136:139], v[64:79]
	v_mfma_f32_32x32x16_bf16 v[64:79], v[88:91], v[140:143], v[64:79]
	v_mfma_f32_32x32x16_bf16 v[64:79], v[92:95], v[144:147], v[64:79]
	v_mfma_f32_32x32x16_bf16 v[64:79], v[96:99], v[148:151], v[64:79]
	v_mfma_f32_32x32x16_bf16 v[64:79], v[100:103], v[152:155], v[64:79]
	ds_read_b128 v[108:111], v250
	ds_read_b128 v[96:99], v250 offset:4096
	ds_read_b128 v[104:107], v251
	ds_read_b128 v[100:103], v251 offset:4096
	ds_read_b128 v[88:91], v250 offset:8192
	ds_read_b128 v[84:87], v250 offset:12288
	ds_read_b128 v[92:95], v251 offset:8192
	ds_read_b128 v[80:83], v251 offset:12288
	v_mfma_f32_32x32x16_bf16 v[64:79], v[112:115], v[156:159], v[64:79]
	s_nop 11
	v_min_f32_e64 v64, -v64, s32
	v_exp_f32_e32 v64, v64
	v_min_f32_e64 v65, -v65, s32
	v_exp_f32_e32 v65, v65
	v_add_f32_e32 v112, 1.0, v64
	v_rcp_f32_e32 v120, v112
	v_add_f32_e32 v112, 1.0, v65
	v_min_f32_e64 v66, -v66, s32
	v_rcp_f32_e32 v121, v112
	v_exp_f32_e32 v112, v66
	v_min_f32_e64 v66, -v67, s32
	v_exp_f32_e32 v67, v66
	v_add_f32_e32 v66, 1.0, v112
	v_rcp_f32_e32 v122, v66
	v_mul_f32_e32 v65, v65, v121
	v_add_f32_e32 v66, 1.0, v67
	v_rcp_f32_e32 v123, v66
	v_cndmask_b32_e64 v66, 1.0, v65, s[14:15]
	v_mul_f32_e32 v65, v112, v122
	v_cndmask_b32_e64 v112, 1.0, v65, s[16:17]
	v_mul_f32_e32 v65, v67, v123
	v_min_f32_e64 v67, -v68, s32
	v_exp_f32_e32 v67, v67
	v_min_f32_e64 v68, -v69, s32
	v_exp_f32_e32 v69, v68
	v_cndmask_b32_e64 v68, 1.0, v65, s[18:19]
	v_add_f32_e32 v65, 1.0, v67
	v_rcp_f32_e32 v124, v65
	v_add_f32_e32 v65, 1.0, v69
	v_rcp_f32_e32 v125, v65
	v_min_f32_e64 v65, -v70, s32
	v_exp_f32_e32 v65, v65
	v_mul_f32_e32 v67, v67, v124
	v_cndmask_b32_e64 v70, 1.0, v67, s[20:21]
	v_mul_f32_e32 v67, v69, v125
	v_add_f32_e32 v69, 1.0, v65
	v_rcp_f32_e32 v126, v69
	v_min_f32_e64 v69, -v71, s32
	v_exp_f32_e32 v69, v69
	v_mul_f32_e32 v65, v65, v126
	v_cndmask_b32_e64 v115, 1.0, v65, s[24:25]
	v_cndmask_b32_e64 v114, 1.0, v67, s[22:23]
	v_add_f32_e32 v65, 1.0, v69
	v_rcp_f32_e32 v127, v65
	v_min_f32_e64 v65, -v72, s32
	v_exp_f32_e32 v65, v65
	v_min_f32_e64 v67, -v73, s32
	v_exp_f32_e32 v67, v67
	v_mul_f32_e32 v69, v69, v127
	v_add_f32_e32 v71, 1.0, v65
	v_rcp_f32_e32 v160, v71
	v_add_f32_e32 v71, 1.0, v67
	v_rcp_f32_e32 v161, v71
	v_cndmask_b32_e64 v71, 1.0, v69, s[26:27]
	v_mul_f32_e32 v65, v65, v160
	v_cndmask_b32_e64 v72, 1.0, v65, s[28:29]
	v_mul_f32_e32 v65, v67, v161
	v_min_f32_e64 v67, -v74, s32
	v_exp_f32_e32 v67, v67
	v_min_f32_e64 v69, -v75, s32
	v_exp_f32_e32 v69, v69
	v_cndmask_b32_e64 v74, 1.0, v65, s[30:31]
	v_add_f32_e32 v65, 1.0, v67
	v_rcp_f32_e32 v162, v65
	v_add_f32_e32 v65, 1.0, v69
	v_rcp_f32_e32 v163, v65
	v_min_f32_e64 v65, -v76, s32
	v_exp_f32_e32 v65, v65
	v_mul_f32_e32 v67, v67, v162
	v_cndmask_b32_e64 v75, 1.0, v67, s[34:35]
	v_mul_f32_e32 v67, v69, v163
	v_add_f32_e32 v69, 1.0, v65
	v_rcp_f32_e32 v164, v69
	v_min_f32_e64 v69, -v77, s32
	v_exp_f32_e32 v69, v69
	v_mul_f32_e32 v65, v65, v164
	v_cndmask_b32_e64 v76, 1.0, v65, s[38:39]
	v_cndmask_b32_e64 v73, 1.0, v67, s[36:37]
	v_add_f32_e32 v65, 1.0, v69
	v_rcp_f32_e32 v165, v65
	v_min_f32_e64 v65, -v78, s32
	v_exp_f32_e32 v65, v65
	v_min_f32_e64 v67, -v79, s32
	v_exp_f32_e32 v67, v67
	v_mul_f32_e32 v69, v69, v165
	v_add_f32_e32 v77, 1.0, v65
	v_rcp_f32_e32 v166, v77
	v_add_f32_e32 v77, 1.0, v67
	v_rcp_f32_e32 v167, v77
	v_cndmask_b32_e64 v78, 1.0, v69, s[40:41]
	v_mul_f32_e32 v65, v65, v166
	v_cndmask_b32_e64 v79, 1.0, v65, s[42:43]
	v_mul_f32_e32 v65, v67, v167
	v_and_b32_e32 v67, 64, v219
	v_cndmask_b32_e64 v77, 1.0, v65, s[44:45]
	v_xor_b32_e32 v65, 32, v219
	v_add_u32_e32 v67, 64, v67
	v_cmp_lt_i32_e32 vcc, v65, v67
	v_pk_mul_f32 v[116:117], v[74:75], v[72:73]
	v_mul_f32_e32 v64, v64, v120
	v_mul_f32_e32 v65, v116, v117
	v_pk_mul_f32 v[116:117], v[78:79], v[76:77]
	v_mov_b32_e32 v72, v65
	s_nop 1
	v_permlane32_swap_b32_e32 v65, v72
	v_mul_f32_e32 v69, v116, v117
	v_mov_b32_e32 v76, v69
	s_nop 1
	v_permlane32_swap_b32_e32 v69, v76
	v_pk_mul_f32 v[116:117], v[114:115], v[70:71]
	v_cndmask_b32_e64 v64, 1.0, v64, s[12:13]
	v_pk_mul_f32 v[116:117], v[116:117], v[116:117] op_sel:[0,1] op_sel_hi:[1,0]
	v_mov_b32_e32 v67, v116
	s_nop 1
	v_permlane32_swap_b32_e32 v116, v67
	s_waitcnt lgkmcnt(0)
	v_mul_f32_e32 v113, v65, v72
	v_mul_f32_e32 v65, v69, v76
	v_mul_f32_e32 v69, v197, v65
	v_mov_b32_e32 v65, v116
	v_pk_mul_f32 v[64:65], v[64:65], v[66:67]
	v_pk_mul_f32 v[116:117], v[112:113], v[68:69]
	v_cndmask_b32_e64 v113, 1.0, v67, s[10:11]
	v_pk_mul_f32 v[118:119], v[64:65], v[116:117]
	v_mov_b32_e32 v116, v118
	s_nop 1
	v_permlane32_swap_b32_e32 v118, v116
	v_cndmask_b32_e64 v67, 1.0, v72, s[10:11]
	v_cndmask_b32_e64 v65, 0, v121, s[14:15]
	v_cndmask_b32_e64 v121, 0, v123, s[18:19]
	v_cndmask_b32_e64 v123, 0, v125, s[22:23]
	s_waitcnt lgkmcnt(0)
; DEV f32x16 mfma32(bf16x8 a, bf16x8 b, f32x16 c) { return __builtin_amdgcn_mfma_f32_32x32x16_bf16(a, b, c, 0, 0, 0); }
; template <bool DIAG>
; DEV void sb_tile(const char* lk, const char* lv, const int ko0, const int vo0, const bf16x8 (&qf)[8], f32x16 (&O)[4], float& accp,
;                  const int l31, const int hh) {
;     ...
;   for (int q = 0; q < 4; ++q) { gp[q] = (om[4 * q] * om[4 * q + 1]) * (om[4 * q + 2] * om[4 * q + 3]); pp[q] = __shfl_xor(gp[q], 32); tot[q] = gp[q] * pp[q]; }
;   float suf[4];
;   suf[3] = accp; suf[2] = suf[3] * tot[3]; suf[1] = suf[2] * tot[2]; suf[0] = suf[1] * tot[1];
;   accp = suf[0] * tot[0];
;   f32x16 w;
; #pragma unroll
;   for (int q = 0; q < 4; ++q) {
;     float a = suf[q] * (hh == 0 ? pp[q] : 1.f);
;     w[4 * q + 3] = be[4 * q + 3] * a; a *= om[4 * q + 3];
;     w[4 * q + 2] = be[4 * q + 2] * a; a *= om[4 * q + 2];
;     w[4 * q + 1] = be[4 * q + 1] * a; a *= om[4 * q + 1];
;     w[4 * q + 0] = be[4 * q + 0] * a;
;   }
;   const bf16x8 w0 = cvt8<0>(w), w1 = cvt8<1>(w);
; #pragma unroll
;   for (int d = 0; d < 4; ++d) { O[d] = mfma32(vf[d][0], w0, O[d]); O[d] = mfma32(vf[d][1], w1, O[d]); }
	v_cndmask_b32_e64 v70, 1.0, v116, s[10:11]
	v_cndmask_b32_e64 v125, 0, v127, s[26:27]
	v_cndmask_b32_e64 v127, 0, v161, s[30:31]
	v_cndmask_b32_e64 v161, 0, v163, s[36:37]
	v_cndmask_b32_e64 v163, 0, v165, s[40:41]
	v_cndmask_b32_e64 v165, 0, v167, s[44:45]
	v_mul_f32_e32 v167, v67, v69
	v_mul_f32_e32 v69, v70, v119
	v_mul_f32_e32 v68, v68, v69
	v_mul_f32_e32 v67, v112, v68
	v_cndmask_b32_e64 v64, 0, v120, s[12:13]
	v_cndmask_b32_e64 v120, 0, v122, s[16:17]
	v_mul_f32_e32 v66, v66, v67
	v_pk_mul_f32 v[64:65], v[64:65], v[66:67]
	v_pk_mul_f32 v[66:67], v[120:121], v[68:69]
	v_mul_f32_e32 v69, v113, v117
	v_mul_f32_e32 v68, v71, v69
	v_mul_f32_e32 v71, v115, v68
	v_cndmask_b32_e64 v122, 0, v124, s[20:21]
	v_cndmask_b32_e64 v124, 0, v126, s[24:25]
	v_mul_f32_e32 v70, v114, v71
	v_pk_mul_f32 v[70:71], v[122:123], v[70:71]
	v_pk_mul_f32 v[68:69], v[124:125], v[68:69]
	v_cvt_pk_bf16_f32 v64, v64, v65
	v_cvt_pk_bf16_f32 v65, v66, v67
	v_cvt_pk_bf16_f32 v66, v70, v71
	v_cvt_pk_bf16_f32 v67, v68, v69
	v_cndmask_b32_e64 v76, 1.0, v76, s[10:11]
	v_mul_f32_e32 v113, v197, v76
	v_mfma_f32_32x32x16_bf16 v[48:63], v[108:111], v[64:67], v[48:63]
	v_cndmask_b32_e64 v126, 0, v160, s[28:29]
	v_cndmask_b32_e64 v160, 0, v162, s[34:35]
	v_cndmask_b32_e64 v162, 0, v164, s[38:39]
	v_cndmask_b32_e64 v164, 0, v166, s[42:43]
	v_mul_f32_e32 v166, v73, v167
	v_mul_f32_e32 v112, v113, v77
	v_mul_f32_e32 v75, v75, v166
	v_mfma_f32_32x32x16_bf16 v[32:47], v[96:99], v[64:67], v[32:47]
	v_mul_f32_e32 v69, v79, v112
	v_mul_f32_e32 v74, v74, v75
	v_mul_f32_e32 v68, v78, v69
	v_mul_f32_e64 v72, v160, v166
	v_mul_f32_e64 v73, v161, v167
	v_pk_mul_f32 v[74:75], v[126:127], v[74:75]
	v_pk_mul_f32 v[76:77], v[164:165], v[112:113]
	v_pk_mul_f32 v[70:71], v[162:163], v[68:69]
	v_mfma_f32_32x32x16_bf16 v[16:31], v[88:91], v[64:67], v[16:31]
	v_cvt_pk_bf16_f32 v68, v74, v75
	v_cvt_pk_bf16_f32 v69, v72, v73
	v_cvt_pk_bf16_f32 v70, v70, v71
	v_cvt_pk_bf16_f32 v71, v76, v77
	v_mfma_f32_32x32x16_bf16 v[0:15], v[84:87], v[64:67], v[0:15]
	v_mul_f32_e32 v64, v118, v116
	v_mul_f32_e32 v199, v64, v119
	v_mfma_f32_32x32x16_bf16 v[48:63], v[104:107], v[68:71], v[48:63]
	v_mfma_f32_32x32x16_bf16 v[32:47], v[100:103], v[68:71], v[32:47]
	v_mfma_f32_32x32x16_bf16 v[16:31], v[92:95], v[68:71], v[16:31]
	v_mfma_f32_32x32x16_bf16 v[0:15], v[80:83], v[68:71], v[0:15]
	s_nop 10
	v_mov_b64_e32 v[110:111], v[30:31]
	v_mov_b64_e32 v[94:95], v[46:47]
	v_mov_b64_e32 v[78:79], v[62:63]
	v_mov_b64_e32 v[108:109], v[28:29]
	v_mov_b64_e32 v[106:107], v[26:27]
	v_mov_b64_e32 v[104:105], v[24:25]
	v_mov_b64_e32 v[102:103], v[22:23]
	v_mov_b64_e32 v[126:127], v[14:15]
	v_mov_b64_e32 v[124:125], v[12:13]
	v_mov_b64_e32 v[122:123], v[10:11]
	v_mov_b64_e32 v[120:121], v[8:9]
	v_mov_b64_e32 v[118:119], v[6:7]
	v_mov_b64_e32 v[116:117], v[4:5]
	v_mov_b64_e32 v[114:115], v[2:3]
	v_mov_b64_e32 v[112:113], v[0:1]
	v_mov_b64_e32 v[100:101], v[20:21]
	v_mov_b64_e32 v[98:99], v[18:19]
	v_mov_b64_e32 v[96:97], v[16:17]
	v_mov_b64_e32 v[92:93], v[44:45]
	v_mov_b64_e32 v[90:91], v[42:43]
	v_mov_b64_e32 v[88:89], v[40:41]
	v_mov_b64_e32 v[86:87], v[38:39]
	v_mov_b64_e32 v[84:85], v[36:37]
	v_mov_b64_e32 v[82:83], v[34:35]
	v_mov_b64_e32 v[80:81], v[32:33]
	v_mov_b64_e32 v[76:77], v[60:61]
	v_mov_b64_e32 v[74:75], v[58:59]
	v_mov_b64_e32 v[72:73], v[56:57]
	v_mov_b64_e32 v[70:71], v[54:55]
	v_mov_b64_e32 v[68:69], v[52:53]
	v_mov_b64_e32 v[66:67], v[50:51]
	v_mov_b64_e32 v[64:65], v[48:49]
; DEV f32x16 mfma32(bf16x8 a, bf16x8 b, f32x16 c) { return __builtin_amdgcn_mfma_f32_32x32x16_bf16(a, b, c, 0, 0, 0); }
; template <bool DIAG>
; DEV void sb_tile(const char* lk, const char* lv, const int ko0, const int vo0, const bf16x8 (&qf)[8], f32x16 (&O)[4], float& accp,
;                  const int l31, const int hh) {
;   f32x16 z;
;   for (int g = 0; g < 16; ++g) z[g] = 0.f;
;   {
;     bf16x8 kf[8];
; #pragma unroll
;     for (int s = 0; s < 8; ++s) kf[s] = *(const bf16x8*)(lk + (ko0 ^ (32 * s)));
;     __builtin_amdgcn_sched_barrier(0);
; #pragma unroll
;     for (int s = 0; s < 8; ++s) z = mfma32(kf[s], qf[s], z);
;   }
;   bf16x8 vf[4][2];
; #pragma unroll
;   for (int d = 0; d < 4; ++d) { vf[d][0] = *(const bf16x8*)(lv + d * 4096 + vo0); vf[d][1] = *(const bf16x8*)(lv + d * 4096 + (vo0 ^ 32)); }
;   __builtin_amdgcn_sched_barrier(0);
;   float be[16], om[16];
; #pragma unroll
;   for (int g = 0; g < 16; ++g) {
;     const float e = __builtin_amdgcn_exp2f(fminf(-z[g], 120.f));
;     be[g] = __builtin_amdgcn_rcpf(1.f + e);
;     om[g] = e * be[g];
;     if (DIAG) { const int kl = (g & 3) + 8 * (g >> 2) + 4 * hh; if (kl >= l31) { be[g] = 0.f; om[g] = 1.f; } }
;   }
;   float gp[4], pp[4], tot[4];
; #pragma unroll
;   for (int q = 0; q < 4; ++q) { gp[q] = (om[4 * q] * om[4 * q + 1]) * (om[4 * q + 2] * om[4 * q + 3]); pp[q] = __shfl_xor(gp[q], 32); tot[q] = gp[q] * pp[q]; }
;   float suf[4];
;   suf[3] = accp; suf[2] = suf[3] * tot[3]; suf[1] = suf[2] * tot[2]; suf[0] = suf[1] * tot[1];
;   accp = suf[0] * tot[0];
;   f32x16 w;
; #pragma unroll
;   for (int q = 0; q < 4; ++q) {
;     float a = suf[q] * (hh == 0 ? pp[q] : 1.f);
;     w[4 * q + 3] = be[4 * q + 3] * a; a *= om[4 * q + 3];
;     w[4 * q + 2] = be[4 * q + 2] * a; a *= om[4 * q + 2];
;     w[4 * q + 1] = be[4 * q + 1] * a; a *= om[4 * q + 1];
;     w[4 * q + 0] = be[4 * q + 0] * a;
;   }
;   const bf16x8 w0 = cvt8<0>(w), w1 = cvt8<1>(w);
; #pragma unroll
;   for (int d = 0; d < 4; ++d) { O[d] = mfma32(vf[d][0], w0, O[d]); O[d] = mfma32(vf[d][1], w1, O[d]); }
.LBB0_565:
	s_cmp_lg_u32 s88, s69
	s_mov_b64 s[66:67], -1
	s_cbranch_scc0 .LBB0_569
	s_add_i32 s0, s0, 6
	s_cmp_ge_i32 s0, s75
	s_cbranch_scc1 .Lsb_skip_B0
	ds_read_b128 v[0:3], v240
	ds_read_b128 v[16:19], v241
	ds_read_b128 v[20:23], v242
	ds_read_b128 v[24:27], v243
	ds_read_b128 v[28:31], v244
	ds_read_b128 v[32:35], v245
	ds_read_b128 v[36:39], v246
	ds_read_b128 v[40:43], v247
	s_waitcnt lgkmcnt(0)
	v_mfma_f32_32x32x16_bf16 v[0:15], v[0:3], v[128:131], 0
	v_mfma_f32_32x32x16_bf16 v[0:15], v[16:19], v[132:135], v[0:15]
	v_mfma_f32_32x32x16_bf16 v[0:15], v[20:23], v[136:139], v[0:15]
	v_mfma_f32_32x32x16_bf16 v[0:15], v[24:27], v[140:143], v[0:15]
	v_mfma_f32_32x32x16_bf16 v[0:15], v[28:31], v[144:147], v[0:15]
	v_mfma_f32_32x32x16_bf16 v[0:15], v[32:35], v[148:151], v[0:15]
	ds_read_b128 v[28:31], v248
	ds_read_b128 v[16:19], v248 offset:4096
	ds_read_b128 v[24:27], v249
	ds_read_b128 v[20:23], v249 offset:4096
	ds_read_b128 v[168:171], v248 offset:8192
	ds_read_b128 v[164:167], v248 offset:12288
	ds_read_b128 v[172:175], v249 offset:8192
	ds_read_b128 v[160:163], v249 offset:12288
	v_mfma_f32_32x32x16_bf16 v[0:15], v[36:39], v[152:155], v[0:15]
	v_mfma_f32_32x32x16_bf16 v[0:15], v[40:43], v[156:159], v[0:15]
	s_nop 11
	v_min_f32_e64 v4, -v4, s32
	v_exp_f32_e32 v34, v4
	v_min_f32_e64 v4, -v5, s32
	v_exp_f32_e32 v35, v4
	v_add_f32_e32 v4, 1.0, v34
	v_min_f32_e64 v9, -v9, s32
	v_add_f32_e32 v5, 1.0, v35
	v_rcp_f32_e32 v4, v4
	v_rcp_f32_e32 v5, v5
	v_exp_f32_e32 v40, v9
	v_min_f32_e64 v9, -v10, s32
	v_min_f32_e64 v10, -v11, s32
	v_min_f32_e64 v8, -v8, s32
	v_min_f32_e64 v11, -v13, s32
	v_min_f32_e64 v13, -v15, s32
	v_and_b32_e32 v15, 64, v219
	v_exp_f32_e32 v8, v8
	v_exp_f32_e32 v41, v10
	v_min_f32_e64 v10, -v12, s32
	v_exp_f32_e32 v12, v11
	v_min_f32_e64 v11, -v14, s32
	v_xor_b32_e32 v14, 32, v219
	v_add_u32_e32 v15, 64, v15
	v_cmp_lt_i32_e32 vcc, v14, v15
	v_pk_mul_f32 v[34:35], v[34:35], v[4:5]
	v_exp_f32_e32 v9, v9
	v_pk_mul_f32 v[14:15], v[34:35], v[34:35] op_sel_hi:[0,1]
	v_add_f32_e32 v14, 1.0, v8
	v_rcp_f32_e32 v44, v14
	v_add_f32_e32 v14, 1.0, v40
	v_rcp_f32_e32 v46, v14
	v_add_f32_e32 v14, 1.0, v9
	v_rcp_f32_e32 v45, v14
	v_add_f32_e32 v14, 1.0, v41
	v_rcp_f32_e32 v47, v14
	v_exp_f32_e32 v10, v10
	v_exp_f32_e32 v11, v11
	v_exp_f32_e32 v13, v13
	v_pk_mul_f32 v[8:9], v[8:9], v[44:45]
	v_pk_mul_f32 v[40:41], v[40:41], v[46:47]
	v_pk_mul_f32 v[48:49], v[8:9], v[40:41]
	v_add_f32_e32 v8, 1.0, v10
	v_rcp_f32_e32 v50, v8
	v_add_f32_e32 v8, 1.0, v12
	v_rcp_f32_e32 v52, v8
	v_add_f32_e32 v8, 1.0, v11
	v_min_f32_e64 v6, -v6, s32
	v_rcp_f32_e32 v51, v8
	v_add_f32_e32 v8, 1.0, v13
	v_exp_f32_e32 v36, v6
	v_rcp_f32_e32 v53, v8
	v_min_f32_e64 v6, -v7, s32
	v_min_f32_e64 v3, -v3, s32
	v_exp_f32_e32 v37, v6
	v_min_f32_e64 v0, -v0, s32
	v_exp_f32_e32 v198, v3
	v_exp_f32_e32 v32, v0
	v_pk_mul_f32 v[10:11], v[10:11], v[50:51]
	v_pk_mul_f32 v[12:13], v[12:13], v[52:53]
	v_add_f32_e32 v6, 1.0, v36
	v_pk_mul_f32 v[54:55], v[10:11], v[12:13]
	v_add_f32_e32 v7, 1.0, v37
	v_mul_f32_e32 v8, v54, v55
	v_add_f32_e32 v3, 1.0, v198
	v_rcp_f32_e32 v6, v6
	v_rcp_f32_e32 v7, v7
	v_pk_mul_f32 v[48:49], v[48:49], v[48:49] op_sel:[0,1] op_sel_hi:[1,0]
	v_mov_b32_e32 v10, v8
	s_nop 1
	v_permlane32_swap_b32_e32 v8, v10
	v_add_f32_e32 v0, 1.0, v32
	v_min_f32_e64 v2, -v2, s32
	v_rcp_f32_e32 v3, v3
	v_mov_b32_e32 v49, v48
	s_nop 1
	v_permlane32_swap_b32_e32 v48, v49
	v_rcp_f32_e32 v0, v0
	v_min_f32_e64 v1, -v1, s32
	v_exp_f32_e32 v38, v2
	v_exp_f32_e32 v56, v1
	v_pk_mul_f32 v[36:37], v[36:37], v[6:7]
	s_waitcnt lgkmcnt(0)
	v_mul_f32_e32 v55, v8, v10
	v_pk_mul_f32 v[42:43], v[36:37], v[36:37] op_sel_hi:[0,1]
	v_mov_b32_e32 v54, v3
	v_add_f32_e32 v2, 1.0, v38
	v_mov_b32_e32 v33, v15
	v_cndmask_b32_e64 v8, 1.0, v49, s[10:11]
	v_mov_b32_e32 v14, v45
	v_mov_b32_e32 v15, v47
	v_mov_b32_e32 v45, v46
	v_pk_mul_f32 v[46:47], v[198:199], v[54:55]
	v_mov_b32_e32 v42, v0
	v_add_f32_e32 v1, 1.0, v56
	v_rcp_f32_e32 v2, v2
	v_mul_f32_e32 v55, v8, v47
	v_pk_mul_f32 v[32:33], v[32:33], v[42:43]
	v_rcp_f32_e32 v1, v1
	v_mul_f32_e32 v54, v41, v55
	v_mov_b32_e32 v41, v33
	s_nop 1
	v_permlane32_swap_b32_e32 v33, v41
	v_mov_b32_e32 v39, v48
	v_mov_b32_e32 v48, v2
	v_mul_f32_e32 v9, v9, v54
	v_pk_mul_f32 v[38:39], v[38:39], v[48:49]
	v_mul_f32_e32 v8, v40, v9
	v_mul_f32_e32 v40, v56, v1
	v_pk_mul_f32 v[48:49], v[38:39], v[46:47]
	s_waitcnt lgkmcnt(0)
	v_pk_mul_f32 v[32:33], v[32:33], v[40:41]
	v_cndmask_b32_e64 v34, 1.0, v41, s[10:11]
	v_pk_mul_f32 v[32:33], v[32:33], v[48:49]
	v_mov_b32_e32 v39, v32
	s_nop 1
	v_permlane32_swap_b32_e32 v32, v39
	v_cndmask_b32_e64 v10, 1.0, v10, s[10:11]
	v_pk_mul_f32 v[14:15], v[14:15], v[54:55]
	v_pk_mul_f32 v[8:9], v[44:45], v[8:9]
	v_cvt_pk_bf16_f32 v225, v14, v15
	s_waitcnt lgkmcnt(0)
	v_mul_f32_e32 v32, v32, v39
	v_mul_f32_e32 v197, v32, v33
	v_cndmask_b32_e64 v32, 1.0, v39, s[10:11]
	v_mul_f32_e32 v33, v32, v33
	v_mul_f32_e32 v32, v46, v33
	v_pk_mul_f32 v[2:3], v[2:3], v[32:33]
	v_mul_f32_e32 v33, v34, v49
	v_mul_f32_e32 v39, v38, v32
	v_mul_f32_e32 v32, v37, v33
	v_mul_f32_e32 v37, v36, v32
	v_mul_f32_e32 v36, v35, v37
	v_mul_f32_e32 v35, v199, v10
	v_mul_f32_e32 v38, v40, v39
	v_mul_f32_e32 v34, v13, v35
	v_pk_mul_f32 v[0:1], v[0:1], v[38:39]
	v_pk_mul_f32 v[4:5], v[4:5], v[36:37]
	v_pk_mul_f32 v[6:7], v[6:7], v[32:33]
	v_mov_b32_e32 v32, v51
	v_mov_b32_e32 v33, v53
	v_mul_f32_e32 v11, v11, v34
	v_pk_mul_f32 v[32:33], v[32:33], v[34:35]
	v_mov_b32_e32 v51, v52
	v_mul_f32_e32 v10, v12, v11
	v_cvt_pk_bf16_f32 v214, v0, v1
	v_cvt_pk_bf16_f32 v215, v2, v3
	v_cvt_pk_bf16_f32 v216, v4, v5
	v_cvt_pk_bf16_f32 v217, v6, v7
	v_pk_mul_f32 v[10:11], v[50:51], v[10:11]
	v_cvt_pk_bf16_f32 v227, v32, v33
	v_mfma_f32_32x32x16_bf16 v[48:63], v[28:31], v[214:217], v[64:79]
	v_cvt_pk_bf16_f32 v224, v8, v9
	v_cvt_pk_bf16_f32 v226, v10, v11
	v_mfma_f32_32x32x16_bf16 v[32:47], v[16:19], v[214:217], v[80:95]
	s_nop 0
	v_mfma_f32_32x32x16_bf16 v[48:63], v[24:27], v[224:227], v[48:63]
	v_mfma_f32_32x32x16_bf16 v[32:47], v[20:23], v[224:227], v[32:47]
	v_mfma_f32_32x32x16_bf16 v[16:31], v[168:171], v[214:217], v[96:111]
	v_mfma_f32_32x32x16_bf16 v[0:15], v[164:167], v[214:217], v[112:127]
	v_mfma_f32_32x32x16_bf16 v[16:31], v[172:175], v[224:227], v[16:31]
	v_mfma_f32_32x32x16_bf16 v[0:15], v[160:163], v[224:227], v[0:15]

; DEV f32x16 mfma32(bf16x8 a, bf16x8 b, f32x16 c) { return __builtin_amdgcn_mfma_f32_32x32x16_bf16(a, b, c, 0, 0, 0); }
; template <bool DIAG>
; DEV void sb_tile(const char* lk, const char* lv, const int ko0, const int vo0, const bf16x8 (&qf)[8], f32x16 (&O)[4], float& accp,
;                  const int l31, const int hh) {
;   f32x16 z;
;   for (int g = 0; g < 16; ++g) z[g] = 0.f;
;   {
;     bf16x8 kf[8];
; #pragma unroll
;     for (int s = 0; s < 8; ++s) kf[s] = *(const bf16x8*)(lk + (ko0 ^ (32 * s)));
;     __builtin_amdgcn_sched_barrier(0);
; #pragma unroll
;     for (int s = 0; s < 8; ++s) z = mfma32(kf[s], qf[s], z);
;   }
;   bf16x8 vf[4][2];
; #pragma unroll
;   for (int d = 0; d < 4; ++d) { vf[d][0] = *(const bf16x8*)(lv + d * 4096 + vo0); vf[d][1] = *(const bf16x8*)(lv + d * 4096 + (vo0 ^ 32)); }
;   __builtin_amdgcn_sched_barrier(0);
;   float be[16], om[16];
; #pragma unroll
;   for (int g = 0; g < 16; ++g) {
;     const float e = __builtin_amdgcn_exp2f(fminf(-z[g], 120.f));
;     be[g] = __builtin_amdgcn_rcpf(1.f + e);
;     om[g] = e * be[g];
;     if (DIAG) { const int kl = (g & 3) + 8 * (g >> 2) + 4 * hh; if (kl >= l31) { be[g] = 0.f; om[g] = 1.f; } }
;   }
;   float gp[4], pp[4], tot[4];
; #pragma unroll
;   for (int q = 0; q < 4; ++q) { gp[q] = (om[4 * q] * om[4 * q + 1]) * (om[4 * q + 2] * om[4 * q + 3]); pp[q] = __shfl_xor(gp[q], 32); tot[q] = gp[q] * pp[q]; }
;   float suf[4];
;   suf[3] = accp; suf[2] = suf[3] * tot[3]; suf[1] = suf[2] * tot[2]; suf[0] = suf[1] * tot[1];
.LBB0_570:
	s_nop 9
	ds_read_b128 v[0:3], v240
	ds_read_b128 v[16:19], v241
	ds_read_b128 v[20:23], v242
	ds_read_b128 v[24:27], v243
	ds_read_b128 v[28:31], v244
	ds_read_b128 v[32:35], v245
	ds_read_b128 v[36:39], v246
	ds_read_b128 v[48:51], v247
	s_waitcnt lgkmcnt(0)
	v_mfma_f32_32x32x16_bf16 v[0:15], v[0:3], v[128:131], 0
	v_mfma_f32_32x32x16_bf16 v[0:15], v[16:19], v[132:135], v[0:15]
	v_mfma_f32_32x32x16_bf16 v[0:15], v[20:23], v[136:139], v[0:15]
	v_mfma_f32_32x32x16_bf16 v[0:15], v[24:27], v[140:143], v[0:15]
	v_mfma_f32_32x32x16_bf16 v[0:15], v[28:31], v[144:147], v[0:15]
	v_mfma_f32_32x32x16_bf16 v[0:15], v[32:35], v[148:151], v[0:15]
	v_mfma_f32_32x32x16_bf16 v[0:15], v[36:39], v[152:155], v[0:15]
	ds_read_b128 v[44:47], v248
	ds_read_b128 v[32:35], v248 offset:4096
	ds_read_b128 v[40:43], v249
	ds_read_b128 v[36:39], v249 offset:4096
	ds_read_b128 v[24:27], v248 offset:8192
	ds_read_b128 v[20:23], v248 offset:12288
	ds_read_b128 v[28:31], v249 offset:8192
	ds_read_b128 v[16:19], v249 offset:12288
	v_mfma_f32_32x32x16_bf16 v[0:15], v[48:51], v[156:159], v[0:15]
	s_nop 11
	v_min_f32_e64 v0, -v0, s32
	v_exp_f32_e32 v0, v0
	v_min_f32_e64 v1, -v1, s32
	v_exp_f32_e32 v1, v1
	v_add_f32_e32 v48, 1.0, v0
	v_rcp_f32_e32 v56, v48
	v_add_f32_e32 v48, 1.0, v1
	v_min_f32_e64 v2, -v2, s32
	v_rcp_f32_e32 v57, v48
	v_exp_f32_e32 v48, v2
	v_min_f32_e64 v2, -v3, s32
	v_exp_f32_e32 v3, v2
	v_add_f32_e32 v2, 1.0, v48
	v_rcp_f32_e32 v58, v2
	v_mul_f32_e32 v1, v1, v57
	v_add_f32_e32 v2, 1.0, v3
	v_rcp_f32_e32 v59, v2
	v_cndmask_b32_e64 v2, 1.0, v1, s[14:15]
	v_mul_f32_e32 v1, v48, v58
	v_cndmask_b32_e64 v48, 1.0, v1, s[16:17]
	v_mul_f32_e32 v1, v3, v59
	v_min_f32_e64 v3, -v4, s32
	v_exp_f32_e32 v3, v3
	v_min_f32_e64 v4, -v5, s32
	v_exp_f32_e32 v5, v4
	v_cndmask_b32_e64 v4, 1.0, v1, s[18:19]
	v_add_f32_e32 v1, 1.0, v3
	v_rcp_f32_e32 v60, v1
	v_add_f32_e32 v1, 1.0, v5
	v_rcp_f32_e32 v61, v1
	v_min_f32_e64 v1, -v6, s32
	v_exp_f32_e32 v1, v1
	v_mul_f32_e32 v3, v3, v60
	v_cndmask_b32_e64 v6, 1.0, v3, s[20:21]
	v_mul_f32_e32 v3, v5, v61
	v_add_f32_e32 v5, 1.0, v1
	v_rcp_f32_e32 v62, v5
	v_min_f32_e64 v5, -v7, s32
	v_exp_f32_e32 v5, v5
	v_mul_f32_e32 v1, v1, v62
	v_cndmask_b32_e64 v51, 1.0, v1, s[24:25]
	v_cndmask_b32_e64 v50, 1.0, v3, s[22:23]
	v_add_f32_e32 v1, 1.0, v5
	v_rcp_f32_e32 v63, v1
	v_min_f32_e64 v1, -v8, s32
	v_exp_f32_e32 v1, v1
	v_min_f32_e64 v3, -v9, s32
	v_exp_f32_e32 v3, v3
	v_mul_f32_e32 v5, v5, v63
	v_add_f32_e32 v7, 1.0, v1
	v_rcp_f32_e32 v160, v7
	v_add_f32_e32 v7, 1.0, v3
	v_rcp_f32_e32 v161, v7
	v_cndmask_b32_e64 v7, 1.0, v5, s[26:27]
	v_mul_f32_e32 v1, v1, v160
	v_cndmask_b32_e64 v8, 1.0, v1, s[28:29]
	v_mul_f32_e32 v1, v3, v161
	v_min_f32_e64 v3, -v10, s32
	v_exp_f32_e32 v3, v3
	v_min_f32_e64 v5, -v11, s32
	v_exp_f32_e32 v5, v5
	v_cndmask_b32_e64 v10, 1.0, v1, s[30:31]
	v_add_f32_e32 v1, 1.0, v3
	v_rcp_f32_e32 v162, v1
	v_add_f32_e32 v1, 1.0, v5
	v_rcp_f32_e32 v163, v1
	v_min_f32_e64 v1, -v12, s32
	v_exp_f32_e32 v1, v1
	v_mul_f32_e32 v3, v3, v162
	v_cndmask_b32_e64 v11, 1.0, v3, s[34:35]
	v_mul_f32_e32 v3, v5, v163
	v_add_f32_e32 v5, 1.0, v1
	v_rcp_f32_e32 v164, v5
	v_min_f32_e64 v5, -v13, s32
	v_exp_f32_e32 v5, v5
	v_mul_f32_e32 v1, v1, v164
	v_cndmask_b32_e64 v12, 1.0, v1, s[38:39]
	v_cndmask_b32_e64 v9, 1.0, v3, s[36:37]
	v_add_f32_e32 v1, 1.0, v5
	v_rcp_f32_e32 v165, v1
	v_min_f32_e64 v1, -v14, s32
	v_exp_f32_e32 v1, v1
	v_min_f32_e64 v3, -v15, s32
	v_exp_f32_e32 v3, v3
	v_mul_f32_e32 v5, v5, v165
	v_add_f32_e32 v13, 1.0, v1
	v_rcp_f32_e32 v166, v13
	v_add_f32_e32 v13, 1.0, v3
	v_rcp_f32_e32 v167, v13
	v_cndmask_b32_e64 v14, 1.0, v5, s[40:41]
	v_mul_f32_e32 v1, v1, v166
	v_cndmask_b32_e64 v15, 1.0, v1, s[42:43]
	v_mul_f32_e32 v1, v3, v167
	v_and_b32_e32 v3, 64, v219
	v_cndmask_b32_e64 v13, 1.0, v1, s[44:45]
	v_xor_b32_e32 v1, 32, v219
	v_add_u32_e32 v3, 64, v3
	v_cmp_lt_i32_e32 vcc, v1, v3
	v_pk_mul_f32 v[52:53], v[10:11], v[8:9]
	v_mul_f32_e32 v0, v0, v56
	v_mul_f32_e32 v1, v52, v53
	v_pk_mul_f32 v[52:53], v[14:15], v[12:13]
	v_mov_b32_e32 v8, v1
	s_nop 1
	v_permlane32_swap_b32_e32 v1, v8
	v_mul_f32_e32 v5, v52, v53
	v_mov_b32_e32 v12, v5
	s_nop 1
	v_permlane32_swap_b32_e32 v5, v12
	v_pk_mul_f32 v[52:53], v[50:51], v[6:7]
	v_cndmask_b32_e64 v0, 1.0, v0, s[12:13]
	v_pk_mul_f32 v[52:53], v[52:53], v[52:53] op_sel:[0,1] op_sel_hi:[1,0]
	v_mov_b32_e32 v3, v52
	s_nop 1
	v_permlane32_swap_b32_e32 v52, v3
	s_waitcnt lgkmcnt(0)
	v_mul_f32_e32 v49, v1, v8
	v_mul_f32_e32 v1, v5, v12
	v_mul_f32_e32 v5, v199, v1
	v_mov_b32_e32 v1, v52
	v_pk_mul_f32 v[0:1], v[0:1], v[2:3]
	v_pk_mul_f32 v[52:53], v[48:49], v[4:5]
	v_cndmask_b32_e64 v49, 1.0, v3, s[10:11]
	v_pk_mul_f32 v[54:55], v[0:1], v[52:53]
	v_mov_b32_e32 v52, v54
	s_nop 1
	v_permlane32_swap_b32_e32 v54, v52
	v_cndmask_b32_e64 v3, 1.0, v8, s[10:11]
	v_cndmask_b32_e64 v1, 0, v57, s[14:15]
	v_cndmask_b32_e64 v57, 0, v59, s[18:19]
	v_cndmask_b32_e64 v59, 0, v61, s[22:23]
	s_waitcnt lgkmcnt(0)
; DEV f32x16 mfma32(bf16x8 a, bf16x8 b, f32x16 c) { return __builtin_amdgcn_mfma_f32_32x32x16_bf16(a, b, c, 0, 0, 0); }
; template <bool DIAG>
; DEV void sb_tile(const char* lk, const char* lv, const int ko0, const int vo0, const bf16x8 (&qf)[8], f32x16 (&O)[4], float& accp,
;                  const int l31, const int hh) {
;     ...
;     if (DIAG) { const int kl = (g & 3) + 8 * (g >> 2) + 4 * hh; if (kl >= l31) { be[g] = 0.f; om[g] = 1.f; } }
;   }
;   float gp[4], pp[4], tot[4];
; #pragma unroll
;   for (int q = 0; q < 4; ++q) { gp[q] = (om[4 * q] * om[4 * q + 1]) * (om[4 * q + 2] * om[4 * q + 3]); pp[q] = __shfl_xor(gp[q], 32); tot[q] = gp[q] * pp[q]; }
;   float suf[4];
;   suf[3] = accp; suf[2] = suf[3] * tot[3]; suf[1] = suf[2] * tot[2]; suf[0] = suf[1] * tot[1];
;   accp = suf[0] * tot[0];
;   f32x16 w;
; #pragma unroll
;   for (int q = 0; q < 4; ++q) {
;     float a = suf[q] * (hh == 0 ? pp[q] : 1.f);
;     w[4 * q + 3] = be[4 * q + 3] * a; a *= om[4 * q + 3];
;     w[4 * q + 2] = be[4 * q + 2] * a; a *= om[4 * q + 2];
;     w[4 * q + 1] = be[4 * q + 1] * a; a *= om[4 * q + 1];
;     w[4 * q + 0] = be[4 * q + 0] * a;
;   }
;   const bf16x8 w0 = cvt8<0>(w), w1 = cvt8<1>(w);
; #pragma unroll
;   for (int d = 0; d < 4; ++d) { O[d] = mfma32(vf[d][0], w0, O[d]); O[d] = mfma32(vf[d][1], w1, O[d]); }
	v_cndmask_b32_e64 v6, 1.0, v52, s[10:11]
	v_cndmask_b32_e64 v61, 0, v63, s[26:27]
	v_cndmask_b32_e64 v63, 0, v161, s[30:31]
	v_cndmask_b32_e64 v161, 0, v163, s[36:37]
	v_cndmask_b32_e64 v163, 0, v165, s[40:41]
	v_cndmask_b32_e64 v165, 0, v167, s[44:45]
	v_mul_f32_e32 v167, v3, v5
	v_mul_f32_e32 v5, v6, v55
	v_mul_f32_e32 v4, v4, v5
	v_mul_f32_e32 v3, v48, v4
	v_cndmask_b32_e64 v0, 0, v56, s[12:13]
	v_cndmask_b32_e64 v56, 0, v58, s[16:17]
	v_mul_f32_e32 v2, v2, v3
	v_pk_mul_f32 v[0:1], v[0:1], v[2:3]
	v_pk_mul_f32 v[2:3], v[56:57], v[4:5]
	v_mul_f32_e32 v5, v49, v53
	v_mul_f32_e32 v4, v7, v5
	v_mul_f32_e32 v7, v51, v4
	v_cndmask_b32_e64 v58, 0, v60, s[20:21]
	v_cndmask_b32_e64 v60, 0, v62, s[24:25]
	v_mul_f32_e32 v6, v50, v7
	v_pk_mul_f32 v[6:7], v[58:59], v[6:7]
	v_pk_mul_f32 v[4:5], v[60:61], v[4:5]
	v_cvt_pk_bf16_f32 v0, v0, v1
	v_cvt_pk_bf16_f32 v1, v2, v3
	v_cvt_pk_bf16_f32 v2, v6, v7
	v_cvt_pk_bf16_f32 v3, v4, v5
	v_cndmask_b32_e64 v12, 1.0, v12, s[10:11]
	v_mul_f32_e32 v49, v199, v12
	v_mfma_f32_32x32x16_bf16 v[64:79], v[44:47], v[0:3], v[64:79]
	v_cndmask_b32_e64 v62, 0, v160, s[28:29]
	v_cndmask_b32_e64 v160, 0, v162, s[34:35]
	v_cndmask_b32_e64 v162, 0, v164, s[38:39]
	v_cndmask_b32_e64 v164, 0, v166, s[42:43]
	v_mul_f32_e32 v166, v9, v167
	v_mul_f32_e32 v48, v49, v13
	v_mul_f32_e32 v11, v11, v166
	v_mfma_f32_32x32x16_bf16 v[80:95], v[32:35], v[0:3], v[80:95]
	v_mul_f32_e32 v5, v15, v48
	v_mul_f32_e32 v10, v10, v11
	v_mul_f32_e32 v4, v14, v5
	v_mul_f32_e64 v8, v160, v166
	v_mul_f32_e64 v9, v161, v167
	v_pk_mul_f32 v[10:11], v[62:63], v[10:11]
	v_pk_mul_f32 v[12:13], v[164:165], v[48:49]
	v_pk_mul_f32 v[6:7], v[162:163], v[4:5]
	v_mfma_f32_32x32x16_bf16 v[96:111], v[24:27], v[0:3], v[96:111]
	v_cvt_pk_bf16_f32 v4, v10, v11
	v_cvt_pk_bf16_f32 v5, v8, v9
	v_cvt_pk_bf16_f32 v6, v6, v7
	v_cvt_pk_bf16_f32 v7, v12, v13
	v_mfma_f32_32x32x16_bf16 v[112:127], v[20:23], v[0:3], v[112:127]
	v_mul_f32_e32 v0, v54, v52
	v_mul_f32_e32 v197, v0, v55
	v_mfma_f32_32x32x16_bf16 v[64:79], v[40:43], v[4:7], v[64:79]
	v_mfma_f32_32x32x16_bf16 v[80:95], v[36:39], v[4:7], v[80:95]
	s_nop 10
	v_mov_b64_e32 v[48:49], v[64:65]
	v_mov_b64_e32 v[50:51], v[66:67]
	v_mov_b64_e32 v[52:53], v[68:69]
	v_mov_b64_e32 v[54:55], v[70:71]
	v_mov_b64_e32 v[56:57], v[72:73]
	v_mov_b64_e32 v[58:59], v[74:75]
	v_mov_b64_e32 v[60:61], v[76:77]
	v_mfma_f32_32x32x16_bf16 v[96:111], v[28:31], v[4:7], v[96:111]
	v_mov_b64_e32 v[32:33], v[80:81]
	v_mov_b64_e32 v[34:35], v[82:83]
	v_mov_b64_e32 v[36:37], v[84:85]
	v_mov_b64_e32 v[38:39], v[86:87]
	v_mov_b64_e32 v[40:41], v[88:89]
	v_mov_b64_e32 v[42:43], v[90:91]
	v_mov_b64_e32 v[44:45], v[92:93]
	v_mfma_f32_32x32x16_bf16 v[112:127], v[16:19], v[4:7], v[112:127]
	s_nop 3
	v_mov_b64_e32 v[16:17], v[96:97]
	v_mov_b64_e32 v[18:19], v[98:99]
	v_mov_b64_e32 v[20:21], v[100:101]
	v_mov_b64_e32 v[22:23], v[102:103]
	v_mov_b64_e32 v[24:25], v[104:105]
	v_mov_b64_e32 v[26:27], v[106:107]
	v_mov_b64_e32 v[28:29], v[108:109]
	s_nop 0
	v_mov_b64_e32 v[0:1], v[112:113]
	v_mov_b64_e32 v[2:3], v[114:115]
	v_mov_b64_e32 v[4:5], v[116:117]
	v_mov_b64_e32 v[6:7], v[118:119]
	v_mov_b64_e32 v[8:9], v[120:121]
	v_mov_b64_e32 v[10:11], v[122:123]
	v_mov_b64_e32 v[12:13], v[124:125]
	v_mov_b64_e32 v[14:15], v[126:127]
	v_mov_b64_e32 v[30:31], v[110:111]
	v_mov_b64_e32 v[46:47], v[94:95]
	v_mov_b64_e32 v[62:63], v[78:79]
	s_branch .LBB0_542
.Lsb_skip_A0:
	v_mov_b64_e32 v[78:79], v[62:63]
	v_mov_b64_e32 v[94:95], v[46:47]
	v_mov_b64_e32 v[110:111], v[30:31]
	v_mov_b64_e32 v[126:127], v[14:15]
	v_mov_b32_e32 v199, v197
	v_mov_b64_e32 v[76:77], v[60:61]
	v_mov_b64_e32 v[74:75], v[58:59]
	v_mov_b64_e32 v[72:73], v[56:57]
	v_mov_b64_e32 v[70:71], v[54:55]
	v_mov_b64_e32 v[68:69], v[52:53]
	v_mov_b64_e32 v[66:67], v[50:51]
	v_mov_b64_e32 v[64:65], v[48:49]
	v_mov_b64_e32 v[92:93], v[44:45]
	v_mov_b64_e32 v[90:91], v[42:43]
	v_mov_b64_e32 v[88:89], v[40:41]
	v_mov_b64_e32 v[86:87], v[38:39]
	v_mov_b64_e32 v[84:85], v[36:37]
	v_mov_b64_e32 v[82:83], v[34:35]
	v_mov_b64_e32 v[80:81], v[32:33]
	v_mov_b64_e32 v[108:109], v[28:29]
	v_mov_b64_e32 v[106:107], v[26:27]
	v_mov_b64_e32 v[104:105], v[24:25]
	v_mov_b64_e32 v[102:103], v[22:23]
	v_mov_b64_e32 v[100:101], v[20:21]
	v_mov_b64_e32 v[98:99], v[18:19]
	v_mov_b64_e32 v[96:97], v[16:17]
	v_mov_b64_e32 v[124:125], v[12:13]
	v_mov_b64_e32 v[122:123], v[10:11]
	v_mov_b64_e32 v[120:121], v[8:9]
	v_mov_b64_e32 v[118:119], v[6:7]
	v_mov_b64_e32 v[116:117], v[4:5]
	v_mov_b64_e32 v[114:115], v[2:3]
	v_mov_b64_e32 v[112:113], v[0:1]
	s_branch .LBB0_562
	s_nop 0
	s_nop 0
	s_nop 0
	s_nop 0
	s_nop 0
	s_nop 0
	s_nop 0
	s_nop 0
	s_nop 0
	s_nop 0
	s_nop 0
	s_nop 0
	s_nop 0
	s_nop 0
	s_nop 0
	s_nop 0
	s_nop 0
	s_nop 0
	s_nop 0
	s_nop 0
	s_nop 0
	s_nop 0
	s_nop 0
	s_nop 0
	s_nop 0
	s_nop 0
	s_nop 0
	s_nop 0
	s_nop 0
	s_nop 0
	s_nop 0
	s_nop 0
	s_nop 0
	s_nop 0
	s_nop 0
	s_nop 0
	s_nop 0
	s_nop 0
	s_nop 0
	s_nop 0
	s_nop 0
	s_nop 0
	s_nop 0
	s_nop 0
	s_nop 0
	s_nop 0
	s_nop 0
	s_nop 0
	s_nop 0
	s_nop 0
	s_nop 0
	s_nop 0
	s_nop 0
	s_nop 0
	s_nop 0
	s_nop 0
	s_nop 0
	s_nop 0
	s_nop 0
	s_nop 0

; template <bool DIAG>
; DEV void sb_tile(const char* lk, const char* lv, const int ko0, const int vo0, const bf16x8 (&qf)[8], f32x16 (&O)[4], float& accp,
;                  const int l31, const int hh) {
;   f32x16 z;
;   for (int g = 0; g < 16; ++g) z[g] = 0.f;
;   {
;     bf16x8 kf[8];
; #pragma unroll
;     for (int s = 0; s < 8; ++s) kf[s] = *(const bf16x8*)(lk + (ko0 ^ (32 * s)));
;     __builtin_amdgcn_sched_barrier(0);
; #pragma unroll
;     for (int s = 0; s < 8; ++s) z = mfma32(kf[s], qf[s], z);
;   }
;   bf16x8 vf[4][2];
; #pragma unroll
;   for (int d = 0; d < 4; ++d) { vf[d][0] = *(const bf16x8*)(lv + d * 4096 + vo0); vf[d][1] = *(const bf16x8*)(lv + d * 4096 + (vo0 ^ 32)); }
;   __builtin_amdgcn_sched_barrier(0);
;   float be[16], om[16];
; #pragma unroll
;   for (int g = 0; g < 16; ++g) {
;     const float e = __builtin_amdgcn_exp2f(fminf(-z[g], 120.f));
;     be[g] = __builtin_amdgcn_rcpf(1.f + e);
;     om[g] = e * be[g];
;     if (DIAG) { const int kl = (g & 3) + 8 * (g >> 2) + 4 * hh; if (kl >= l31) { be[g] = 0.f; om[g] = 1.f; } }
;   }
;   float gp[4], pp[4], tot[4];
; #pragma unroll
;   for (int q = 0; q < 4; ++q) { gp[q] = (om[4 * q] * om[4 * q + 1]) * (om[4 * q + 2] * om[4 * q + 3]); pp[q] = __shfl_xor(gp[q], 32); tot[q] = gp[q] * pp[q]; }
;   float suf[4];
;   suf[3] = accp; suf[2] = suf[3] * tot[3]; suf[1] = suf[2] * tot[2]; suf[0] = suf[1] * tot[1];
;   accp = suf[0] * tot[0];
;   f32x16 w;
; #pragma unroll
;   for (int q = 0; q < 4; ++q) {
;     float a = suf[q] * (hh == 0 ? pp[q] : 1.f);
;     w[4 * q + 3] = be[4 * q + 3] * a; a *= om[4 * q + 3];
;     w[4 * q + 2] = be[4 * q + 2] * a; a *= om[4 * q + 2];
;     w[4 * q + 1] = be[4 * q + 1] * a; a *= om[4 * q + 1];
;     w[4 * q + 0] = be[4 * q + 0] * a;
;   }
;   const bf16x8 w0 = cvt8<0>(w), w1 = cvt8<1>(w);
; #pragma unroll
;   for (int d = 0; d < 4; ++d) { O[d] = mfma32(vf[d][0], w0, O[d]); O[d] = mfma32(vf[d][1], w1, O[d]); }
; DEV void sb_block(const Params& p, int item) {
;     ...
;     { const int jn = j > 3 ? j - 3 : 0; SB_DMA(jn, (n + 3) & 3); }
;     const char* lb_ = smem + buf * 32768;
;     int ko0 = KO0, vo0 = VO0;
;     asm volatile("" : "+v"(ko0), "+v"(vo0));
;     if (2 * j + 1 == qt) sb_tile<true>(lb_ + 32 * 256, lb_, ko0, vo0 ^ 64, qf, O, accp, l31, hh);
;     else if (2 * j + 1 < qt) sb_tile<false>(lb_ + 32 * 256, lb_, ko0, vo0 ^ 64, qf, O, accp, l31, hh);
.LBB0_1211:
	s_and_b32 s66, s33, 0x18000
	s_add_i32 s92, s66, 0
	v_add_u32_e32 v240, s92, v228
	v_add_u32_e32 v241, s92, v229
	v_add_u32_e32 v242, s92, v230
	v_add_u32_e32 v243, s92, v231
	v_add_u32_e32 v244, s92, v232
	v_add_u32_e32 v245, s92, v233
	v_add_u32_e32 v246, s92, v234
	v_add_u32_e32 v247, s92, v235
	v_add_u32_e32 v248, s92, v236
	v_add_u32_e32 v249, s92, v237
	v_add_u32_e32 v250, s92, v238
	v_add_u32_e32 v251, s92, v239
	s_add_i32 s90, s74, s69
	s_cmp_lg_u32 s89, s69
	s_mov_b64 s[66:67], -1
	s_cbranch_scc0 .LBB0_1215
	s_add_i32 s66, s90, 7
	s_cmp_ge_i32 s66, s76
	s_cbranch_scc1 .Lsb_skip_A1
	ds_read_b128 v[64:67], v240 offset:8192
	ds_read_b128 v[80:83], v241 offset:8192
	ds_read_b128 v[84:87], v242 offset:8192
	ds_read_b128 v[88:91], v243 offset:8192
	ds_read_b128 v[92:95], v244 offset:8192
	ds_read_b128 v[96:99], v245 offset:8192
	ds_read_b128 v[100:103], v246 offset:8192
	ds_read_b128 v[104:107], v247 offset:8192
	s_waitcnt lgkmcnt(0)
	v_mfma_f32_32x32x16_bf16 v[64:79], v[64:67], v[128:131], 0
	v_mfma_f32_32x32x16_bf16 v[64:79], v[80:83], v[132:135], v[64:79]
	v_mfma_f32_32x32x16_bf16 v[64:79], v[84:87], v[136:139], v[64:79]
	v_mfma_f32_32x32x16_bf16 v[64:79], v[88:91], v[140:143], v[64:79]
	v_mfma_f32_32x32x16_bf16 v[64:79], v[92:95], v[144:147], v[64:79]
	v_mfma_f32_32x32x16_bf16 v[64:79], v[96:99], v[148:151], v[64:79]
	v_mfma_f32_32x32x16_bf16 v[64:79], v[100:103], v[152:155], v[64:79]
	ds_read_b128 v[84:87], v250
	ds_read_b128 v[96:99], v250 offset:4096
	ds_read_b128 v[80:83], v251
	ds_read_b128 v[100:103], v251 offset:4096
	ds_read_b128 v[112:115], v250 offset:8192
	ds_read_b128 v[164:167], v250 offset:12288
	ds_read_b128 v[116:119], v251 offset:8192
	ds_read_b128 v[160:163], v251 offset:12288
	v_mfma_f32_32x32x16_bf16 v[64:79], v[104:107], v[156:159], v[64:79]
	s_nop 11
	v_min_f32_e64 v68, -v68, s32
	v_exp_f32_e32 v90, v68
	v_min_f32_e64 v68, -v69, s32
	v_exp_f32_e32 v91, v68
	v_add_f32_e32 v68, 1.0, v90
	v_min_f32_e64 v73, -v73, s32
	v_add_f32_e32 v69, 1.0, v91
	v_rcp_f32_e32 v68, v68
	v_rcp_f32_e32 v69, v69
	v_exp_f32_e32 v104, v73
	v_min_f32_e64 v73, -v74, s32
	v_min_f32_e64 v74, -v75, s32
	v_min_f32_e64 v72, -v72, s32
	v_min_f32_e64 v75, -v77, s32
	v_min_f32_e64 v77, -v79, s32
	v_exp_f32_e32 v72, v72
	v_exp_f32_e32 v105, v74
	v_min_f32_e64 v74, -v76, s32
	v_exp_f32_e32 v76, v75
	v_min_f32_e64 v75, -v78, s32
	v_pk_mul_f32 v[90:91], v[90:91], v[68:69]
	v_exp_f32_e32 v73, v73
	v_pk_mul_f32 v[78:79], v[90:91], v[90:91] op_sel_hi:[0,1]
	v_add_f32_e32 v78, 1.0, v72
	v_rcp_f32_e32 v108, v78
	v_add_f32_e32 v78, 1.0, v104
	v_rcp_f32_e32 v110, v78
	v_add_f32_e32 v78, 1.0, v73
	v_rcp_f32_e32 v109, v78
	v_add_f32_e32 v78, 1.0, v105
	v_rcp_f32_e32 v111, v78
	v_exp_f32_e32 v74, v74
	v_exp_f32_e32 v75, v75
	v_exp_f32_e32 v77, v77
	v_pk_mul_f32 v[72:73], v[72:73], v[108:109]
	v_pk_mul_f32 v[104:105], v[104:105], v[110:111]
	v_pk_mul_f32 v[120:121], v[72:73], v[104:105]
	v_add_f32_e32 v72, 1.0, v74
	v_rcp_f32_e32 v122, v72
	v_add_f32_e32 v72, 1.0, v76
	v_rcp_f32_e32 v124, v72
	v_add_f32_e32 v72, 1.0, v75
	v_min_f32_e64 v70, -v70, s32
	v_rcp_f32_e32 v123, v72
	v_add_f32_e32 v72, 1.0, v77
	v_exp_f32_e32 v92, v70
	v_rcp_f32_e32 v125, v72
	v_min_f32_e64 v70, -v71, s32
	v_min_f32_e64 v67, -v67, s32
	v_exp_f32_e32 v93, v70
	v_min_f32_e64 v64, -v64, s32
	v_exp_f32_e32 v196, v67
	v_exp_f32_e32 v88, v64
	v_pk_mul_f32 v[74:75], v[74:75], v[122:123]
	v_pk_mul_f32 v[76:77], v[76:77], v[124:125]
	v_add_f32_e32 v70, 1.0, v92
	v_pk_mul_f32 v[126:127], v[74:75], v[76:77]
	v_add_f32_e32 v71, 1.0, v93
	v_mul_f32_e32 v72, v126, v127
	v_add_f32_e32 v67, 1.0, v196
	v_rcp_f32_e32 v70, v70
	v_rcp_f32_e32 v71, v71
	v_pk_mul_f32 v[120:121], v[120:121], v[120:121] op_sel:[0,1] op_sel_hi:[1,0]
	v_mov_b32_e32 v74, v72
	s_nop 1
	v_permlane32_swap_b32_e32 v72, v74
	v_add_f32_e32 v64, 1.0, v88
	v_min_f32_e64 v66, -v66, s32
	v_rcp_f32_e32 v67, v67
	v_mov_b32_e32 v121, v120
	s_nop 1
	v_permlane32_swap_b32_e32 v120, v121
	v_rcp_f32_e32 v64, v64
	v_min_f32_e64 v65, -v65, s32
	v_exp_f32_e32 v94, v66
	v_exp_f32_e32 v169, v65
	v_pk_mul_f32 v[92:93], v[92:93], v[70:71]
	s_waitcnt lgkmcnt(0)
	v_mul_f32_e32 v127, v72, v74
	v_pk_mul_f32 v[106:107], v[92:93], v[92:93] op_sel_hi:[0,1]
	v_mov_b32_e32 v126, v67
	v_add_f32_e32 v66, 1.0, v94
	v_mov_b32_e32 v89, v79
	v_cndmask_b32_e64 v72, 1.0, v121, s[10:11]
	v_mov_b32_e32 v78, v109
	v_mov_b32_e32 v79, v111
	v_mov_b32_e32 v109, v110
	v_pk_mul_f32 v[110:111], v[196:197], v[126:127]
	v_mov_b32_e32 v106, v64
	v_add_f32_e32 v65, 1.0, v169
	v_rcp_f32_e32 v66, v66
	v_mul_f32_e32 v127, v72, v111
	v_pk_mul_f32 v[88:89], v[88:89], v[106:107]
	v_rcp_f32_e32 v65, v65
	v_mul_f32_e32 v126, v105, v127
	v_mov_b32_e32 v105, v89
	s_nop 1
	v_permlane32_swap_b32_e32 v89, v105
	v_mov_b32_e32 v95, v120
	v_mov_b32_e32 v120, v66
	v_mul_f32_e32 v73, v73, v126
	v_pk_mul_f32 v[94:95], v[94:95], v[120:121]
	v_mul_f32_e32 v72, v104, v73
	v_mul_f32_e32 v104, v169, v65
	v_pk_mul_f32 v[120:121], v[94:95], v[110:111]
	s_waitcnt lgkmcnt(0)
	v_pk_mul_f32 v[88:89], v[88:89], v[104:105]
	v_cndmask_b32_e64 v90, 1.0, v105, s[10:11]
	v_pk_mul_f32 v[88:89], v[88:89], v[120:121]
	v_mov_b32_e32 v95, v88
	s_nop 1
	v_permlane32_swap_b32_e32 v88, v95
	v_cndmask_b32_e64 v74, 1.0, v74, s[10:11]
	v_pk_mul_f32 v[78:79], v[78:79], v[126:127]
	v_pk_mul_f32 v[72:73], v[108:109], v[72:73]
	v_cvt_pk_bf16_f32 v209, v78, v79
	s_waitcnt lgkmcnt(0)
	v_mul_f32_e32 v88, v88, v95
	v_mul_f32_e32 v199, v88, v89
	v_cndmask_b32_e64 v88, 1.0, v95, s[10:11]
	v_mul_f32_e32 v89, v88, v89
	v_mul_f32_e32 v88, v110, v89
	v_pk_mul_f32 v[66:67], v[66:67], v[88:89]
	v_mul_f32_e32 v89, v90, v121
	v_mul_f32_e32 v95, v94, v88
	v_mul_f32_e32 v88, v93, v89
	v_mul_f32_e32 v93, v92, v88
	v_mul_f32_e32 v92, v91, v93
	v_mul_f32_e32 v91, v197, v74
	v_mul_f32_e32 v90, v77, v91
	v_mul_f32_e32 v94, v104, v95
	v_mul_f32_e32 v75, v75, v90
	v_pk_mul_f32 v[64:65], v[64:65], v[94:95]
	v_pk_mul_f32 v[68:69], v[68:69], v[92:93]
	v_pk_mul_f32 v[70:71], v[70:71], v[88:89]
	v_mov_b32_e32 v88, v123
	v_mov_b32_e32 v123, v124
	v_mul_f32_e32 v74, v76, v75
	v_pk_mul_f32 v[74:75], v[122:123], v[74:75]
	v_cvt_pk_bf16_f32 v170, v64, v65
	v_cvt_pk_bf16_f32 v171, v66, v67
	v_cvt_pk_bf16_f32 v172, v68, v69
	v_cvt_pk_bf16_f32 v173, v70, v71
	v_cvt_pk_bf16_f32 v208, v72, v73
	v_cvt_pk_bf16_f32 v210, v74, v75
	v_mfma_f32_32x32x16_bf16 v[64:79], v[84:87], v[170:173], v[48:63]
	v_mov_b32_e32 v89, v125
	v_mul_f32_e64 v88, v88, v90
	v_mul_f32_e64 v89, v89, v91
	v_cvt_pk_bf16_f32 v211, v88, v89
	s_nop 1
	v_mfma_f32_32x32x16_bf16 v[64:79], v[80:83], v[208:211], v[64:79]
	v_mfma_f32_32x32x16_bf16 v[80:95], v[96:99], v[170:173], v[32:47]
	v_mfma_f32_32x32x16_bf16 v[80:95], v[100:103], v[208:211], v[80:95]
	v_mfma_f32_32x32x16_bf16 v[96:111], v[112:115], v[170:173], v[16:31]
	v_mfma_f32_32x32x16_bf16 v[96:111], v[116:119], v[208:211], v[96:111]
	v_mfma_f32_32x32x16_bf16 v[112:127], v[164:167], v[170:173], v[0:15]
	v_mfma_f32_32x32x16_bf16 v[112:127], v[160:163], v[208:211], v[112:127]

; DEV f32x16 mfma32(bf16x8 a, bf16x8 b, f32x16 c) { return __builtin_amdgcn_mfma_f32_32x32x16_bf16(a, b, c, 0, 0, 0); }
; template <bool DIAG>
; DEV void sb_tile(const char* lk, const char* lv, const int ko0, const int vo0, const bf16x8 (&qf)[8], f32x16 (&O)[4], float& accp,
;                  const int l31, const int hh) {
;   f32x16 z;
;   for (int g = 0; g < 16; ++g) z[g] = 0.f;
;   {
;     bf16x8 kf[8];
; #pragma unroll
;     for (int s = 0; s < 8; ++s) kf[s] = *(const bf16x8*)(lk + (ko0 ^ (32 * s)));
;     __builtin_amdgcn_sched_barrier(0);
; #pragma unroll
;     for (int s = 0; s < 8; ++s) z = mfma32(kf[s], qf[s], z);
;   }
;   bf16x8 vf[4][2];
; #pragma unroll
;   for (int d = 0; d < 4; ++d) { vf[d][0] = *(const bf16x8*)(lv + d * 4096 + vo0); vf[d][1] = *(const bf16x8*)(lv + d * 4096 + (vo0 ^ 32)); }
;   __builtin_amdgcn_sched_barrier(0);
;   float be[16], om[16];
; #pragma unroll
;   for (int g = 0; g < 16; ++g) {
;     const float e = __builtin_amdgcn_exp2f(fminf(-z[g], 120.f));
;     be[g] = __builtin_amdgcn_rcpf(1.f + e);
;     om[g] = e * be[g];
;     if (DIAG) { const int kl = (g & 3) + 8 * (g >> 2) + 4 * hh; if (kl >= l31) { be[g] = 0.f; om[g] = 1.f; } }
;   }
;   float gp[4], pp[4], tot[4];
; #pragma unroll
;   for (int q = 0; q < 4; ++q) { gp[q] = (om[4 * q] * om[4 * q + 1]) * (om[4 * q + 2] * om[4 * q + 3]); pp[q] = __shfl_xor(gp[q], 32); tot[q] = gp[q] * pp[q]; }
;   float suf[4];
;   suf[3] = accp; suf[2] = suf[3] * tot[3]; suf[1] = suf[2] * tot[2]; suf[0] = suf[1] * tot[1];
;   accp = suf[0] * tot[0];
;   f32x16 w;
; #pragma unroll
;   for (int q = 0; q < 4; ++q) {
;     float a = suf[q] * (hh == 0 ? pp[q] : 1.f);
;     w[4 * q + 3] = be[4 * q + 3] * a; a *= om[4 * q + 3];
;     w[4 * q + 2] = be[4 * q + 2] * a; a *= om[4 * q + 2];
;     w[4 * q + 1] = be[4 * q + 1] * a; a *= om[4 * q + 1];
;     w[4 * q + 0] = be[4 * q + 0] * a;
;   }
;   const bf16x8 w0 = cvt8<0>(w), w1 = cvt8<1>(w);
; #pragma unroll
;   for (int d = 0; d < 4; ++d) { O[d] = mfma32(vf[d][0], w0, O[d]); O[d] = mfma32(vf[d][1], w1, O[d]); }
.LBB0_1217:
	s_cmp_lg_u32 s88, s69
	s_mov_b64 s[66:67], -1
	s_cbranch_scc0 .LBB0_1221
	s_add_i32 s90, s90, 6
	s_cmp_ge_i32 s90, s76
	s_cbranch_scc1 .Lsb_skip_B1
	ds_read_b128 v[0:3], v240
	ds_read_b128 v[16:19], v241
	ds_read_b128 v[20:23], v242
	ds_read_b128 v[24:27], v243
	ds_read_b128 v[28:31], v244
	ds_read_b128 v[32:35], v245
	ds_read_b128 v[36:39], v246
	ds_read_b128 v[40:43], v247
	s_waitcnt lgkmcnt(0)
	v_mfma_f32_32x32x16_bf16 v[0:15], v[0:3], v[128:131], 0
	v_mfma_f32_32x32x16_bf16 v[0:15], v[16:19], v[132:135], v[0:15]
	v_mfma_f32_32x32x16_bf16 v[0:15], v[20:23], v[136:139], v[0:15]
	v_mfma_f32_32x32x16_bf16 v[0:15], v[24:27], v[140:143], v[0:15]
	v_mfma_f32_32x32x16_bf16 v[0:15], v[28:31], v[144:147], v[0:15]
	v_mfma_f32_32x32x16_bf16 v[0:15], v[32:35], v[148:151], v[0:15]
	ds_read_b128 v[28:31], v248
	ds_read_b128 v[16:19], v248 offset:4096
	ds_read_b128 v[24:27], v249
	ds_read_b128 v[20:23], v249 offset:4096
	ds_read_b128 v[168:171], v248 offset:8192
	ds_read_b128 v[164:167], v248 offset:12288
	ds_read_b128 v[172:175], v249 offset:8192
	ds_read_b128 v[160:163], v249 offset:12288
	v_mfma_f32_32x32x16_bf16 v[0:15], v[36:39], v[152:155], v[0:15]
	v_mfma_f32_32x32x16_bf16 v[0:15], v[40:43], v[156:159], v[0:15]
	s_nop 11
	v_min_f32_e64 v4, -v4, s32
	v_exp_f32_e32 v34, v4
	v_min_f32_e64 v4, -v5, s32
	v_exp_f32_e32 v35, v4
	v_add_f32_e32 v4, 1.0, v34
	v_min_f32_e64 v9, -v9, s32
	v_add_f32_e32 v5, 1.0, v35
	v_rcp_f32_e32 v4, v4
	v_rcp_f32_e32 v5, v5
	v_exp_f32_e32 v40, v9
	v_min_f32_e64 v9, -v10, s32
	v_min_f32_e64 v10, -v11, s32
	v_min_f32_e64 v8, -v8, s32
	v_min_f32_e64 v11, -v13, s32
	v_min_f32_e64 v13, -v15, s32
	v_and_b32_e32 v15, 64, v219
	v_exp_f32_e32 v8, v8
	v_exp_f32_e32 v41, v10
	v_min_f32_e64 v10, -v12, s32
	v_exp_f32_e32 v12, v11
	v_min_f32_e64 v11, -v14, s32
	v_xor_b32_e32 v14, 32, v219
	v_add_u32_e32 v15, 64, v15
	v_cmp_lt_i32_e32 vcc, v14, v15
	v_pk_mul_f32 v[34:35], v[34:35], v[4:5]
	v_exp_f32_e32 v9, v9
	v_pk_mul_f32 v[14:15], v[34:35], v[34:35] op_sel_hi:[0,1]
	v_add_f32_e32 v14, 1.0, v8
	v_rcp_f32_e32 v44, v14
	v_add_f32_e32 v14, 1.0, v40
	v_rcp_f32_e32 v46, v14
	v_add_f32_e32 v14, 1.0, v9
	v_rcp_f32_e32 v45, v14
	v_add_f32_e32 v14, 1.0, v41
	v_rcp_f32_e32 v47, v14
	v_exp_f32_e32 v10, v10
	v_exp_f32_e32 v11, v11
	v_exp_f32_e32 v13, v13
	v_pk_mul_f32 v[8:9], v[8:9], v[44:45]
	v_pk_mul_f32 v[40:41], v[40:41], v[46:47]
	v_pk_mul_f32 v[48:49], v[8:9], v[40:41]
	v_add_f32_e32 v8, 1.0, v10
	v_rcp_f32_e32 v50, v8
	v_add_f32_e32 v8, 1.0, v12
	v_rcp_f32_e32 v52, v8
	v_add_f32_e32 v8, 1.0, v11
	v_min_f32_e64 v6, -v6, s32
	v_rcp_f32_e32 v51, v8
	v_add_f32_e32 v8, 1.0, v13
	v_exp_f32_e32 v36, v6
	v_rcp_f32_e32 v53, v8
	v_min_f32_e64 v6, -v7, s32
	v_min_f32_e64 v3, -v3, s32
	v_exp_f32_e32 v37, v6
	v_min_f32_e64 v0, -v0, s32
	v_exp_f32_e32 v198, v3
	v_exp_f32_e32 v32, v0
	v_pk_mul_f32 v[10:11], v[10:11], v[50:51]
	v_pk_mul_f32 v[12:13], v[12:13], v[52:53]
	v_add_f32_e32 v6, 1.0, v36
	v_pk_mul_f32 v[54:55], v[10:11], v[12:13]
	v_add_f32_e32 v7, 1.0, v37
	v_mul_f32_e32 v8, v54, v55
	v_add_f32_e32 v3, 1.0, v198
	v_rcp_f32_e32 v6, v6
	v_rcp_f32_e32 v7, v7
	v_pk_mul_f32 v[48:49], v[48:49], v[48:49] op_sel:[0,1] op_sel_hi:[1,0]
	v_mov_b32_e32 v10, v8
	s_nop 1
	v_permlane32_swap_b32_e32 v8, v10
	v_add_f32_e32 v0, 1.0, v32
	v_min_f32_e64 v2, -v2, s32
	v_rcp_f32_e32 v3, v3
	v_mov_b32_e32 v49, v48
	s_nop 1
	v_permlane32_swap_b32_e32 v48, v49
	v_rcp_f32_e32 v0, v0
	v_min_f32_e64 v1, -v1, s32
	v_exp_f32_e32 v38, v2
	v_exp_f32_e32 v56, v1
	v_pk_mul_f32 v[36:37], v[36:37], v[6:7]
	s_waitcnt lgkmcnt(0)
	v_mul_f32_e32 v55, v8, v10
	v_pk_mul_f32 v[42:43], v[36:37], v[36:37] op_sel_hi:[0,1]
	v_mov_b32_e32 v54, v3
	v_add_f32_e32 v2, 1.0, v38
	v_mov_b32_e32 v33, v15
	v_cndmask_b32_e64 v8, 1.0, v49, s[10:11]
	v_mov_b32_e32 v14, v45
	v_mov_b32_e32 v15, v47
	v_mov_b32_e32 v45, v46
	v_pk_mul_f32 v[46:47], v[198:199], v[54:55]
	v_mov_b32_e32 v42, v0
	v_add_f32_e32 v1, 1.0, v56
	v_rcp_f32_e32 v2, v2
	v_mul_f32_e32 v55, v8, v47
	v_pk_mul_f32 v[32:33], v[32:33], v[42:43]
	v_rcp_f32_e32 v1, v1
	v_mul_f32_e32 v54, v41, v55
	v_mov_b32_e32 v41, v33
	s_nop 1
	v_permlane32_swap_b32_e32 v33, v41
	v_mov_b32_e32 v39, v48
	v_mov_b32_e32 v48, v2
	v_mul_f32_e32 v9, v9, v54
	v_pk_mul_f32 v[38:39], v[38:39], v[48:49]
	v_mul_f32_e32 v8, v40, v9
	v_mul_f32_e32 v40, v56, v1
	v_pk_mul_f32 v[48:49], v[38:39], v[46:47]
	s_waitcnt lgkmcnt(0)
	v_pk_mul_f32 v[32:33], v[32:33], v[40:41]
	v_cndmask_b32_e64 v34, 1.0, v41, s[10:11]
	v_pk_mul_f32 v[32:33], v[32:33], v[48:49]
	v_mov_b32_e32 v39, v32
	s_nop 1
	v_permlane32_swap_b32_e32 v32, v39
	v_cndmask_b32_e64 v10, 1.0, v10, s[10:11]
	v_pk_mul_f32 v[14:15], v[14:15], v[54:55]
	v_pk_mul_f32 v[8:9], v[44:45], v[8:9]
	v_cvt_pk_bf16_f32 v225, v14, v15
	s_waitcnt lgkmcnt(0)
	v_mul_f32_e32 v32, v32, v39
	v_mul_f32_e32 v197, v32, v33
	v_cndmask_b32_e64 v32, 1.0, v39, s[10:11]
	v_mul_f32_e32 v33, v32, v33
	v_mul_f32_e32 v32, v46, v33
	v_pk_mul_f32 v[2:3], v[2:3], v[32:33]
	v_mul_f32_e32 v33, v34, v49
	v_mul_f32_e32 v39, v38, v32
	v_mul_f32_e32 v32, v37, v33
	v_mul_f32_e32 v37, v36, v32
	v_mul_f32_e32 v36, v35, v37
	v_mul_f32_e32 v35, v199, v10
	v_mul_f32_e32 v38, v40, v39
	v_mul_f32_e32 v34, v13, v35
	v_pk_mul_f32 v[0:1], v[0:1], v[38:39]
	v_pk_mul_f32 v[4:5], v[4:5], v[36:37]
	v_pk_mul_f32 v[6:7], v[6:7], v[32:33]
	v_mov_b32_e32 v32, v51
	v_mov_b32_e32 v33, v53
	v_mul_f32_e32 v11, v11, v34
	v_pk_mul_f32 v[32:33], v[32:33], v[34:35]
	v_mov_b32_e32 v51, v52
	v_mul_f32_e32 v10, v12, v11
	v_cvt_pk_bf16_f32 v214, v0, v1
	v_cvt_pk_bf16_f32 v215, v2, v3
	v_cvt_pk_bf16_f32 v216, v4, v5
	v_cvt_pk_bf16_f32 v217, v6, v7
	v_pk_mul_f32 v[10:11], v[50:51], v[10:11]
	v_cvt_pk_bf16_f32 v227, v32, v33
	v_mfma_f32_32x32x16_bf16 v[48:63], v[28:31], v[214:217], v[64:79]
	v_cvt_pk_bf16_f32 v224, v8, v9
	v_cvt_pk_bf16_f32 v226, v10, v11
	v_mfma_f32_32x32x16_bf16 v[32:47], v[16:19], v[214:217], v[80:95]
	s_nop 0
	v_mfma_f32_32x32x16_bf16 v[48:63], v[24:27], v[224:227], v[48:63]
	v_mfma_f32_32x32x16_bf16 v[32:47], v[20:23], v[224:227], v[32:47]
	v_mfma_f32_32x32x16_bf16 v[16:31], v[168:171], v[214:217], v[96:111]
	v_mfma_f32_32x32x16_bf16 v[0:15], v[164:167], v[214:217], v[112:127]
	v_mfma_f32_32x32x16_bf16 v[16:31], v[172:175], v[224:227], v[16:31]
	v_mfma_f32_32x32x16_bf16 v[0:15], v[160:163], v[224:227], v[0:15]
